# SwiGLU fp8 epilogues of FFN1-up and FFN2-up (direct path) rewritten with packed f32 math (same ops re-associated, fewer VALU instr) on top of r1
# baseline (speedup 1.0000x reference)
; __device__ __forceinline__ float silu_mul(float a, float b) { return a * b * __builtin_amdgcn_rcpf(1.0f + __expf(-a)); }
; __device__ __forceinline__ unsigned cvt4_fp8(float a, float b, float c, float d) {
;     a = __builtin_fminf(__builtin_fmaxf(a, -448.f), 448.f); b = __builtin_fminf(__builtin_fmaxf(b, -448.f), 448.f);
;     c = __builtin_fminf(__builtin_fmaxf(c, -448.f), 448.f); d = __builtin_fminf(__builtin_fmaxf(d, -448.f), 448.f);
;     int w = 0; w = __builtin_amdgcn_cvt_pk_fp8_f32(a, b, w, false); w = __builtin_amdgcn_cvt_pk_fp8_f32(c, d, w, true); return (unsigned)w; }
;     __device__ __forceinline__ void operator()(const f32x4 (&acc)[2][2][4][2], const Unit& u, int wr, int wc, int fr, int fq) const {
;         const int row0 = u.pm * BM + wr * 64 + fr, col0 = u.pn * HALF + wc * 32 + 8 * fq;
;         const float ib = inv * st;
; #pragma unroll
;         for (int ai = 0; ai < 2; ++ai)
; #pragma unroll
;             for (int m = 0; m < 4; ++m) { unsigned char* rowp = O + (size_t)(row0 + ai * HALF + m * 16) * ldc + col0;
;                 const f32x4 a0 = acc[ai][0][m][0] * inv, a1 = acc[ai][0][m][1] * inv, b0 = acc[ai][1][m][0] * ib, b1 = acc[ai][1][m][1] * ib;
;                 u32x2 w;
;                 w.x = cvt4_fp8(silu_mul(a0[0], b0[0]), silu_mul(a0[1], b0[1]), silu_mul(a0[2], b0[2]), silu_mul(a0[3], b0[3]));
;                 w.y = cvt4_fp8(silu_mul(a1[0], b1[0]), silu_mul(a1[1], b1[1]), silu_mul(a1[2], b1[2]), silu_mul(a1[3], b1[3]));
;                 *(u32x2*)rowp = w; }
.LBB0_228:
	v_mov_b32_e32 v20, s16
	v_mov_b32_e32 v24, s18
	v_mul_f32_e32 v24, s16, v24
	v_mul_f32_e32 v20, 0xbfb8aa3b, v20
	v_rcp_f32_e32 v24, v24
	s_nop 1
	v_lshl_add_u32 v6, s72, 8, v165
	v_lshl_or_b32 v2, s27, 7, v191
	v_mov_b64_e32 v[4:5], s[58:59]
	v_ashrrev_i32_e32 v3, 31, v2
	v_mad_i64_i32 v[10:11], s[74:75], v6, s97, v[4:5]
	v_lshl_add_u64 v[10:11], v[10:11], 0, v[2:3]
	v_pk_mul_f32 v[12:13], v[158:159], v[20:21] op_sel_hi:[1,0]
	v_pk_mul_f32 v[14:15], v[160:161], v[20:21] op_sel_hi:[1,0]
	v_pk_mul_f32 v[16:17], v[154:155], v[20:21] op_sel_hi:[1,0]
	v_pk_mul_f32 v[18:19], v[156:157], v[20:21] op_sel_hi:[1,0]
	v_exp_f32_e32 v12, v12
	v_exp_f32_e32 v13, v13
	v_exp_f32_e32 v14, v14
	v_exp_f32_e32 v15, v15
	v_exp_f32_e32 v16, v16
	v_exp_f32_e32 v17, v17
	v_exp_f32_e32 v18, v18
	v_exp_f32_e32 v19, v19
	v_pk_mul_f32 v[158:159], v[158:159], v[150:151]
	v_pk_mul_f32 v[160:161], v[160:161], v[152:153]
	v_pk_mul_f32 v[154:155], v[154:155], v[146:147]
	v_pk_mul_f32 v[156:157], v[156:157], v[148:149]
	v_pk_fma_f32 v[12:13], v[12:13], v[24:25], v[24:25] op_sel_hi:[1,0,0]
	v_pk_fma_f32 v[14:15], v[14:15], v[24:25], v[24:25] op_sel_hi:[1,0,0]
	v_pk_fma_f32 v[16:17], v[16:17], v[24:25], v[24:25] op_sel_hi:[1,0,0]
	v_pk_fma_f32 v[18:19], v[18:19], v[24:25], v[24:25] op_sel_hi:[1,0,0]
	v_rcp_f32_e32 v12, v12
	v_rcp_f32_e32 v13, v13
	v_rcp_f32_e32 v14, v14
	v_rcp_f32_e32 v15, v15
	v_rcp_f32_e32 v16, v16
	v_rcp_f32_e32 v17, v17
	v_rcp_f32_e32 v18, v18
	v_rcp_f32_e32 v19, v19
	v_pk_mul_f32 v[158:159], v[158:159], v[12:13]
	v_pk_mul_f32 v[160:161], v[160:161], v[14:15]
	v_pk_mul_f32 v[154:155], v[154:155], v[16:17]
	v_pk_mul_f32 v[156:157], v[156:157], v[18:19]
	v_med3_f32 v158, v158, s26, v195
	v_med3_f32 v159, v159, s26, v195
	v_med3_f32 v160, v160, s26, v195
	v_med3_f32 v161, v161, s26, v195
	v_med3_f32 v154, v154, s26, v195
	v_med3_f32 v155, v155, s26, v195
	v_med3_f32 v156, v156, s26, v195
	v_med3_f32 v157, v157, s26, v195
	v_cvt_pk_fp8_f32 v8, v158, v159
	v_cvt_pk_fp8_f32 v9, v154, v155
	v_cvt_pk_fp8_f32 v8, v160, v161 op_sel:[0,0,1]
	v_cvt_pk_fp8_f32 v9, v156, v157 op_sel:[0,0,1]
	s_nop 1
	global_store_dwordx2 v[10:11], v[8:9], off
	v_or_b32_e32 v7, 16, v6
	v_mad_i64_i32 v[10:11], s[74:75], v7, s97, v[4:5]
	v_lshl_add_u64 v[10:11], v[10:11], 0, v[2:3]
	v_pk_mul_f32 v[12:13], v[142:143], v[20:21] op_sel_hi:[1,0]
	v_pk_mul_f32 v[14:15], v[144:145], v[20:21] op_sel_hi:[1,0]
	v_pk_mul_f32 v[16:17], v[138:139], v[20:21] op_sel_hi:[1,0]
	v_pk_mul_f32 v[18:19], v[140:141], v[20:21] op_sel_hi:[1,0]
	v_exp_f32_e32 v12, v12
	v_exp_f32_e32 v13, v13
	v_exp_f32_e32 v14, v14
	v_exp_f32_e32 v15, v15
	v_exp_f32_e32 v16, v16
	v_exp_f32_e32 v17, v17
	v_exp_f32_e32 v18, v18
	v_exp_f32_e32 v19, v19
	v_pk_mul_f32 v[142:143], v[142:143], v[134:135]
	v_pk_mul_f32 v[144:145], v[144:145], v[136:137]
	v_pk_mul_f32 v[138:139], v[138:139], v[130:131]
	v_pk_mul_f32 v[140:141], v[140:141], v[132:133]
	v_pk_fma_f32 v[12:13], v[12:13], v[24:25], v[24:25] op_sel_hi:[1,0,0]
	v_pk_fma_f32 v[14:15], v[14:15], v[24:25], v[24:25] op_sel_hi:[1,0,0]
	v_pk_fma_f32 v[16:17], v[16:17], v[24:25], v[24:25] op_sel_hi:[1,0,0]
	v_pk_fma_f32 v[18:19], v[18:19], v[24:25], v[24:25] op_sel_hi:[1,0,0]
	v_rcp_f32_e32 v12, v12
	v_rcp_f32_e32 v13, v13
	v_rcp_f32_e32 v14, v14
	v_rcp_f32_e32 v15, v15
	v_rcp_f32_e32 v16, v16
	v_rcp_f32_e32 v17, v17
	v_rcp_f32_e32 v18, v18
	v_rcp_f32_e32 v19, v19
	v_pk_mul_f32 v[142:143], v[142:143], v[12:13]
	v_pk_mul_f32 v[144:145], v[144:145], v[14:15]
	v_pk_mul_f32 v[138:139], v[138:139], v[16:17]
	v_pk_mul_f32 v[140:141], v[140:141], v[18:19]
	v_med3_f32 v142, v142, s26, v195
	v_med3_f32 v143, v143, s26, v195
	v_med3_f32 v144, v144, s26, v195
	v_med3_f32 v145, v145, s26, v195
	v_med3_f32 v138, v138, s26, v195
	v_med3_f32 v139, v139, s26, v195
	v_med3_f32 v140, v140, s26, v195
	v_med3_f32 v141, v141, s26, v195
	v_cvt_pk_fp8_f32 v8, v142, v143
	v_cvt_pk_fp8_f32 v9, v138, v139
	v_cvt_pk_fp8_f32 v8, v144, v145 op_sel:[0,0,1]
	v_cvt_pk_fp8_f32 v9, v140, v141 op_sel:[0,0,1]
	s_nop 1
	global_store_dwordx2 v[10:11], v[8:9], off
	v_or_b32_e32 v7, 32, v6
	v_mad_i64_i32 v[10:11], s[74:75], v7, s97, v[4:5]
	v_lshl_add_u64 v[10:11], v[10:11], 0, v[2:3]
	v_pk_mul_f32 v[12:13], v[126:127], v[20:21] op_sel_hi:[1,0]
	v_pk_mul_f32 v[14:15], v[128:129], v[20:21] op_sel_hi:[1,0]
	v_pk_mul_f32 v[16:17], v[122:123], v[20:21] op_sel_hi:[1,0]
	v_pk_mul_f32 v[18:19], v[124:125], v[20:21] op_sel_hi:[1,0]
	v_exp_f32_e32 v12, v12
	v_exp_f32_e32 v13, v13
	v_exp_f32_e32 v14, v14
	v_exp_f32_e32 v15, v15
	v_exp_f32_e32 v16, v16
	v_exp_f32_e32 v17, v17
	v_exp_f32_e32 v18, v18
	v_exp_f32_e32 v19, v19
	v_pk_mul_f32 v[126:127], v[126:127], v[118:119]
	v_pk_mul_f32 v[128:129], v[128:129], v[120:121]
	v_pk_mul_f32 v[122:123], v[122:123], v[114:115]
	v_pk_mul_f32 v[124:125], v[124:125], v[116:117]
	v_pk_fma_f32 v[12:13], v[12:13], v[24:25], v[24:25] op_sel_hi:[1,0,0]
	v_pk_fma_f32 v[14:15], v[14:15], v[24:25], v[24:25] op_sel_hi:[1,0,0]
	v_pk_fma_f32 v[16:17], v[16:17], v[24:25], v[24:25] op_sel_hi:[1,0,0]
	v_pk_fma_f32 v[18:19], v[18:19], v[24:25], v[24:25] op_sel_hi:[1,0,0]
	v_rcp_f32_e32 v12, v12
	v_rcp_f32_e32 v13, v13
	v_rcp_f32_e32 v14, v14
	v_rcp_f32_e32 v15, v15
	v_rcp_f32_e32 v16, v16
	v_rcp_f32_e32 v17, v17
	v_rcp_f32_e32 v18, v18
	v_rcp_f32_e32 v19, v19
	v_pk_mul_f32 v[126:127], v[126:127], v[12:13]
	v_pk_mul_f32 v[128:129], v[128:129], v[14:15]
	v_pk_mul_f32 v[122:123], v[122:123], v[16:17]
	v_pk_mul_f32 v[124:125], v[124:125], v[18:19]
	v_med3_f32 v126, v126, s26, v195
	v_med3_f32 v127, v127, s26, v195
	v_med3_f32 v128, v128, s26, v195
	v_med3_f32 v129, v129, s26, v195
; __device__ __forceinline__ float silu_mul(float a, float b) { return a * b * __builtin_amdgcn_rcpf(1.0f + __expf(-a)); }
;     __device__ __forceinline__ void operator()(const f32x4 (&acc)[2][2][4][2], const Unit& u, int wr, int wc, int fr, int fq) const {
;     ...
;         for (int ai = 0; ai < 2; ++ai)
; #pragma unroll
;             for (int m = 0; m < 4; ++m) { unsigned char* rowp = O + (size_t)(row0 + ai * HALF + m * 16) * ldc + col0;
;                 const f32x4 a0 = acc[ai][0][m][0] * inv, a1 = acc[ai][0][m][1] * inv, b0 = acc[ai][1][m][0] * ib, b1 = acc[ai][1][m][1] * ib;
;                 u32x2 w;
;                 w.x = cvt4_fp8(silu_mul(a0[0], b0[0]), silu_mul(a0[1], b0[1]), silu_mul(a0[2], b0[2]), silu_mul(a0[3], b0[3]));
;                 w.y = cvt4_fp8(silu_mul(a1[0], b1[0]), silu_mul(a1[1], b1[1]), silu_mul(a1[2], b1[2]), silu_mul(a1[3], b1[3]));
;                 *(u32x2*)rowp = w; }
	v_med3_f32 v122, v122, s26, v195
	v_med3_f32 v123, v123, s26, v195
	v_med3_f32 v124, v124, s26, v195
	v_med3_f32 v125, v125, s26, v195
	v_cvt_pk_fp8_f32 v8, v126, v127
	v_cvt_pk_fp8_f32 v9, v122, v123
	v_cvt_pk_fp8_f32 v8, v128, v129 op_sel:[0,0,1]
	v_cvt_pk_fp8_f32 v9, v124, v125 op_sel:[0,0,1]
	s_nop 1
	global_store_dwordx2 v[10:11], v[8:9], off
	v_or_b32_e32 v7, 48, v6
	v_mad_i64_i32 v[10:11], s[74:75], v7, s97, v[4:5]
	v_lshl_add_u64 v[10:11], v[10:11], 0, v[2:3]
	v_pk_mul_f32 v[12:13], v[110:111], v[20:21] op_sel_hi:[1,0]
	v_pk_mul_f32 v[14:15], v[112:113], v[20:21] op_sel_hi:[1,0]
	v_pk_mul_f32 v[16:17], v[106:107], v[20:21] op_sel_hi:[1,0]
	v_pk_mul_f32 v[18:19], v[108:109], v[20:21] op_sel_hi:[1,0]
	v_exp_f32_e32 v12, v12
	v_exp_f32_e32 v13, v13
	v_exp_f32_e32 v14, v14
	v_exp_f32_e32 v15, v15
	v_exp_f32_e32 v16, v16
	v_exp_f32_e32 v17, v17
	v_exp_f32_e32 v18, v18
	v_exp_f32_e32 v19, v19
	v_pk_mul_f32 v[110:111], v[110:111], v[102:103]
	v_pk_mul_f32 v[112:113], v[112:113], v[104:105]
	v_pk_mul_f32 v[106:107], v[106:107], v[98:99]
	v_pk_mul_f32 v[108:109], v[108:109], v[100:101]
	v_pk_fma_f32 v[12:13], v[12:13], v[24:25], v[24:25] op_sel_hi:[1,0,0]
	v_pk_fma_f32 v[14:15], v[14:15], v[24:25], v[24:25] op_sel_hi:[1,0,0]
	v_pk_fma_f32 v[16:17], v[16:17], v[24:25], v[24:25] op_sel_hi:[1,0,0]
	v_pk_fma_f32 v[18:19], v[18:19], v[24:25], v[24:25] op_sel_hi:[1,0,0]
	v_rcp_f32_e32 v12, v12
	v_rcp_f32_e32 v13, v13
	v_rcp_f32_e32 v14, v14
	v_rcp_f32_e32 v15, v15
	v_rcp_f32_e32 v16, v16
	v_rcp_f32_e32 v17, v17
	v_rcp_f32_e32 v18, v18
	v_rcp_f32_e32 v19, v19
	v_pk_mul_f32 v[110:111], v[110:111], v[12:13]
	v_pk_mul_f32 v[112:113], v[112:113], v[14:15]
	v_pk_mul_f32 v[106:107], v[106:107], v[16:17]
	v_pk_mul_f32 v[108:109], v[108:109], v[18:19]
	v_med3_f32 v110, v110, s26, v195
	v_med3_f32 v111, v111, s26, v195
	v_med3_f32 v112, v112, s26, v195
	v_med3_f32 v113, v113, s26, v195
	v_med3_f32 v106, v106, s26, v195
	v_med3_f32 v107, v107, s26, v195
	v_med3_f32 v108, v108, s26, v195
	v_med3_f32 v109, v109, s26, v195
	v_cvt_pk_fp8_f32 v8, v110, v111
	v_cvt_pk_fp8_f32 v9, v106, v107
	v_cvt_pk_fp8_f32 v8, v112, v113 op_sel:[0,0,1]
	v_cvt_pk_fp8_f32 v9, v108, v109 op_sel:[0,0,1]
	s_nop 1
	global_store_dwordx2 v[10:11], v[8:9], off
	v_add_u32_e32 v7, 0x80, v6
	v_mad_i64_i32 v[10:11], s[74:75], v7, s97, v[4:5]
	v_lshl_add_u64 v[10:11], v[10:11], 0, v[2:3]
	v_pk_mul_f32 v[12:13], v[94:95], v[20:21] op_sel_hi:[1,0]
	v_pk_mul_f32 v[14:15], v[96:97], v[20:21] op_sel_hi:[1,0]
	v_pk_mul_f32 v[16:17], v[90:91], v[20:21] op_sel_hi:[1,0]
	v_pk_mul_f32 v[18:19], v[92:93], v[20:21] op_sel_hi:[1,0]
	v_exp_f32_e32 v12, v12
	v_exp_f32_e32 v13, v13
	v_exp_f32_e32 v14, v14
	v_exp_f32_e32 v15, v15
	v_exp_f32_e32 v16, v16
	v_exp_f32_e32 v17, v17
	v_exp_f32_e32 v18, v18
	v_exp_f32_e32 v19, v19
	v_pk_mul_f32 v[94:95], v[94:95], v[86:87]
	v_pk_mul_f32 v[96:97], v[96:97], v[88:89]
	v_pk_mul_f32 v[90:91], v[90:91], v[82:83]
	v_pk_mul_f32 v[92:93], v[92:93], v[84:85]
	v_pk_fma_f32 v[12:13], v[12:13], v[24:25], v[24:25] op_sel_hi:[1,0,0]
	v_pk_fma_f32 v[14:15], v[14:15], v[24:25], v[24:25] op_sel_hi:[1,0,0]
	v_pk_fma_f32 v[16:17], v[16:17], v[24:25], v[24:25] op_sel_hi:[1,0,0]
	v_pk_fma_f32 v[18:19], v[18:19], v[24:25], v[24:25] op_sel_hi:[1,0,0]
	v_rcp_f32_e32 v12, v12
	v_rcp_f32_e32 v13, v13
	v_rcp_f32_e32 v14, v14
	v_rcp_f32_e32 v15, v15
	v_rcp_f32_e32 v16, v16
	v_rcp_f32_e32 v17, v17
	v_rcp_f32_e32 v18, v18
	v_rcp_f32_e32 v19, v19
	v_pk_mul_f32 v[94:95], v[94:95], v[12:13]
	v_pk_mul_f32 v[96:97], v[96:97], v[14:15]
	v_pk_mul_f32 v[90:91], v[90:91], v[16:17]
	v_pk_mul_f32 v[92:93], v[92:93], v[18:19]
	v_med3_f32 v94, v94, s26, v195
	v_med3_f32 v95, v95, s26, v195
	v_med3_f32 v96, v96, s26, v195
	v_med3_f32 v97, v97, s26, v195
	v_med3_f32 v90, v90, s26, v195
	v_med3_f32 v91, v91, s26, v195
	v_med3_f32 v92, v92, s26, v195
	v_med3_f32 v93, v93, s26, v195
	v_cvt_pk_fp8_f32 v8, v94, v95
	v_cvt_pk_fp8_f32 v9, v90, v91
	v_cvt_pk_fp8_f32 v8, v96, v97 op_sel:[0,0,1]
	v_cvt_pk_fp8_f32 v9, v92, v93 op_sel:[0,0,1]
	s_nop 1
	global_store_dwordx2 v[10:11], v[8:9], off
	v_add_u32_e32 v7, 0x90, v6
	v_mad_i64_i32 v[10:11], s[74:75], v7, s97, v[4:5]
	v_lshl_add_u64 v[10:11], v[10:11], 0, v[2:3]
	v_pk_mul_f32 v[12:13], v[78:79], v[20:21] op_sel_hi:[1,0]
	v_pk_mul_f32 v[14:15], v[80:81], v[20:21] op_sel_hi:[1,0]
	v_pk_mul_f32 v[16:17], v[74:75], v[20:21] op_sel_hi:[1,0]
	v_pk_mul_f32 v[18:19], v[76:77], v[20:21] op_sel_hi:[1,0]
	v_exp_f32_e32 v12, v12
	v_exp_f32_e32 v13, v13
	v_exp_f32_e32 v14, v14
	v_exp_f32_e32 v15, v15
	v_exp_f32_e32 v16, v16
	v_exp_f32_e32 v17, v17
	v_exp_f32_e32 v18, v18
	v_exp_f32_e32 v19, v19
	v_pk_mul_f32 v[78:79], v[78:79], v[70:71]
	v_pk_mul_f32 v[80:81], v[80:81], v[72:73]
	v_pk_mul_f32 v[74:75], v[74:75], v[66:67]
	v_pk_mul_f32 v[76:77], v[76:77], v[68:69]
	v_pk_fma_f32 v[12:13], v[12:13], v[24:25], v[24:25] op_sel_hi:[1,0,0]
; __device__ __forceinline__ float silu_mul(float a, float b) { return a * b * __builtin_amdgcn_rcpf(1.0f + __expf(-a)); }
; #define PG8_BAR __builtin_amdgcn_s_barrier()
;     __device__ __forceinline__ void operator()(const f32x4 (&acc)[2][2][4][2], const Unit& u, int wr, int wc, int fr, int fq) const {
;     ...
;         for (int ai = 0; ai < 2; ++ai)
; #pragma unroll
;             for (int m = 0; m < 4; ++m) { unsigned char* rowp = O + (size_t)(row0 + ai * HALF + m * 16) * ldc + col0;
;                 const f32x4 a0 = acc[ai][0][m][0] * inv, a1 = acc[ai][0][m][1] * inv, b0 = acc[ai][1][m][0] * ib, b1 = acc[ai][1][m][1] * ib;
;                 u32x2 w;
;                 w.x = cvt4_fp8(silu_mul(a0[0], b0[0]), silu_mul(a0[1], b0[1]), silu_mul(a0[2], b0[2]), silu_mul(a0[3], b0[3]));
;                 w.y = cvt4_fp8(silu_mul(a1[0], b1[0]), silu_mul(a1[1], b1[1]), silu_mul(a1[2], b1[2]), silu_mul(a1[3], b1[3]));
;                 *(u32x2*)rowp = w; }
;     ...
;         if constexpr (!Epi::AFTER_DRAIN) { E(acc, cur, wr, wc, fr, fq); S.done(cur); }
;         if (!has_next) break;
; #pragma unroll
;         for (int a = 0; a < 2; ++a)
; #pragma unroll
;             for (int b = 0; b < 2; ++b)
; #pragma unroll
;                 for (int m = 0; m < 4; ++m)
; #pragma unroll
;                     for (int n = 0; n < 2; ++n) acc[a][b][m][n] = (f32x4){0.f, 0.f, 0.f, 0.f};
;         cur = nxt; cA = nA0; cB = nB0; ++ui; if constexpr (Sched::SK) { kb = cur.kb; ke = cur.ke; }
;         if constexpr (ALIGN_EPI) { if (wr == 1) PG8_BAR; }
	v_pk_fma_f32 v[14:15], v[14:15], v[24:25], v[24:25] op_sel_hi:[1,0,0]
	v_pk_fma_f32 v[16:17], v[16:17], v[24:25], v[24:25] op_sel_hi:[1,0,0]
	v_pk_fma_f32 v[18:19], v[18:19], v[24:25], v[24:25] op_sel_hi:[1,0,0]
	v_rcp_f32_e32 v12, v12
	v_rcp_f32_e32 v13, v13
	v_rcp_f32_e32 v14, v14
	v_rcp_f32_e32 v15, v15
	v_rcp_f32_e32 v16, v16
	v_rcp_f32_e32 v17, v17
	v_rcp_f32_e32 v18, v18
	v_rcp_f32_e32 v19, v19
	v_pk_mul_f32 v[78:79], v[78:79], v[12:13]
	v_pk_mul_f32 v[80:81], v[80:81], v[14:15]
	v_pk_mul_f32 v[74:75], v[74:75], v[16:17]
	v_pk_mul_f32 v[76:77], v[76:77], v[18:19]
	v_med3_f32 v78, v78, s26, v195
	v_med3_f32 v79, v79, s26, v195
	v_med3_f32 v80, v80, s26, v195
	v_med3_f32 v81, v81, s26, v195
	v_med3_f32 v74, v74, s26, v195
	v_med3_f32 v75, v75, s26, v195
	v_med3_f32 v76, v76, s26, v195
	v_med3_f32 v77, v77, s26, v195
	v_cvt_pk_fp8_f32 v8, v78, v79
	v_cvt_pk_fp8_f32 v9, v74, v75
	v_cvt_pk_fp8_f32 v8, v80, v81 op_sel:[0,0,1]
	v_cvt_pk_fp8_f32 v9, v76, v77 op_sel:[0,0,1]
	s_nop 1
	global_store_dwordx2 v[10:11], v[8:9], off
	v_add_u32_e32 v7, 0xa0, v6
	v_mad_i64_i32 v[10:11], s[74:75], v7, s97, v[4:5]
	v_lshl_add_u64 v[10:11], v[10:11], 0, v[2:3]
	v_pk_mul_f32 v[12:13], v[62:63], v[20:21] op_sel_hi:[1,0]
	v_pk_mul_f32 v[14:15], v[64:65], v[20:21] op_sel_hi:[1,0]
	v_pk_mul_f32 v[16:17], v[58:59], v[20:21] op_sel_hi:[1,0]
	v_pk_mul_f32 v[18:19], v[60:61], v[20:21] op_sel_hi:[1,0]
	v_exp_f32_e32 v12, v12
	v_exp_f32_e32 v13, v13
	v_exp_f32_e32 v14, v14
	v_exp_f32_e32 v15, v15
	v_exp_f32_e32 v16, v16
	v_exp_f32_e32 v17, v17
	v_exp_f32_e32 v18, v18
	v_exp_f32_e32 v19, v19
	v_pk_mul_f32 v[62:63], v[62:63], v[54:55]
	v_pk_mul_f32 v[64:65], v[64:65], v[56:57]
	v_pk_mul_f32 v[58:59], v[58:59], v[50:51]
	v_pk_mul_f32 v[60:61], v[60:61], v[52:53]
	v_pk_fma_f32 v[12:13], v[12:13], v[24:25], v[24:25] op_sel_hi:[1,0,0]
	v_pk_fma_f32 v[14:15], v[14:15], v[24:25], v[24:25] op_sel_hi:[1,0,0]
	v_pk_fma_f32 v[16:17], v[16:17], v[24:25], v[24:25] op_sel_hi:[1,0,0]
	v_pk_fma_f32 v[18:19], v[18:19], v[24:25], v[24:25] op_sel_hi:[1,0,0]
	v_rcp_f32_e32 v12, v12
	v_rcp_f32_e32 v13, v13
	v_rcp_f32_e32 v14, v14
	v_rcp_f32_e32 v15, v15
	v_rcp_f32_e32 v16, v16
	v_rcp_f32_e32 v17, v17
	v_rcp_f32_e32 v18, v18
	v_rcp_f32_e32 v19, v19
	v_pk_mul_f32 v[62:63], v[62:63], v[12:13]
	v_pk_mul_f32 v[64:65], v[64:65], v[14:15]
	v_pk_mul_f32 v[58:59], v[58:59], v[16:17]
	v_pk_mul_f32 v[60:61], v[60:61], v[18:19]
	v_med3_f32 v62, v62, s26, v195
	v_med3_f32 v63, v63, s26, v195
	v_med3_f32 v64, v64, s26, v195
	v_med3_f32 v65, v65, s26, v195
	v_med3_f32 v58, v58, s26, v195
	v_med3_f32 v59, v59, s26, v195
	v_med3_f32 v60, v60, s26, v195
	v_med3_f32 v61, v61, s26, v195
	v_cvt_pk_fp8_f32 v8, v62, v63
	v_cvt_pk_fp8_f32 v9, v58, v59
	v_cvt_pk_fp8_f32 v8, v64, v65 op_sel:[0,0,1]
	v_cvt_pk_fp8_f32 v9, v60, v61 op_sel:[0,0,1]
	s_nop 1
	global_store_dwordx2 v[10:11], v[8:9], off
	v_add_u32_e32 v22, 0xb0, v6
	v_mad_i64_i32 v[4:5], s[74:75], v22, s97, v[4:5]
	v_lshl_add_u64 v[2:3], v[4:5], 0, v[2:3]
	v_pk_mul_f32 v[12:13], v[46:47], v[20:21] op_sel_hi:[1,0]
	v_pk_mul_f32 v[14:15], v[48:49], v[20:21] op_sel_hi:[1,0]
	v_pk_mul_f32 v[16:17], v[42:43], v[20:21] op_sel_hi:[1,0]
	v_pk_mul_f32 v[18:19], v[44:45], v[20:21] op_sel_hi:[1,0]
	v_exp_f32_e32 v12, v12
	v_exp_f32_e32 v13, v13
	v_exp_f32_e32 v14, v14
	v_exp_f32_e32 v15, v15
	v_exp_f32_e32 v16, v16
	v_exp_f32_e32 v17, v17
	v_exp_f32_e32 v18, v18
	v_exp_f32_e32 v19, v19
	v_pk_mul_f32 v[46:47], v[46:47], v[38:39]
	v_pk_mul_f32 v[48:49], v[48:49], v[40:41]
	v_pk_mul_f32 v[42:43], v[42:43], v[34:35]
	v_pk_mul_f32 v[44:45], v[44:45], v[36:37]
	v_pk_fma_f32 v[12:13], v[12:13], v[24:25], v[24:25] op_sel_hi:[1,0,0]
	v_pk_fma_f32 v[14:15], v[14:15], v[24:25], v[24:25] op_sel_hi:[1,0,0]
	v_pk_fma_f32 v[16:17], v[16:17], v[24:25], v[24:25] op_sel_hi:[1,0,0]
	v_pk_fma_f32 v[18:19], v[18:19], v[24:25], v[24:25] op_sel_hi:[1,0,0]
	v_rcp_f32_e32 v12, v12
	v_rcp_f32_e32 v13, v13
	v_rcp_f32_e32 v14, v14
	v_rcp_f32_e32 v15, v15
	v_rcp_f32_e32 v16, v16
	v_rcp_f32_e32 v17, v17
	v_rcp_f32_e32 v18, v18
	v_rcp_f32_e32 v19, v19
	v_pk_mul_f32 v[46:47], v[46:47], v[12:13]
	v_pk_mul_f32 v[48:49], v[48:49], v[14:15]
	v_pk_mul_f32 v[42:43], v[42:43], v[16:17]
	v_pk_mul_f32 v[44:45], v[44:45], v[18:19]
	v_med3_f32 v46, v46, s26, v195
	v_med3_f32 v47, v47, s26, v195
	v_med3_f32 v48, v48, s26, v195
	v_med3_f32 v49, v49, s26, v195
	v_med3_f32 v42, v42, s26, v195
	v_med3_f32 v43, v43, s26, v195
	v_med3_f32 v44, v44, s26, v195
	v_med3_f32 v45, v45, s26, v195
	v_cvt_pk_fp8_f32 v6, v46, v47
	v_cvt_pk_fp8_f32 v7, v42, v43
	v_cvt_pk_fp8_f32 v6, v48, v49 op_sel:[0,0,1]
	v_cvt_pk_fp8_f32 v7, v44, v45 op_sel:[0,0,1]
	s_nop 1
	global_store_dwordx2 v[2:3], v[6:7], off
	s_andn2_b64 vcc, exec, s[2:3]
	s_mov_b64 s[2:3], -1
	s_cbranch_vccnz .LBB0_221
	s_andn2_b64 vcc, exec, s[8:9]
	s_cbranch_vccnz .LBB0_220
	s_barrier
	s_branch .LBB0_220

; __device__ __forceinline__ float silu_mul(float a, float b) { return a * b * __builtin_amdgcn_rcpf(1.0f + __expf(-a)); }
; __device__ __forceinline__ unsigned cvt4_fp8(float a, float b, float c, float d) {
;     a = __builtin_fminf(__builtin_fmaxf(a, -448.f), 448.f); b = __builtin_fminf(__builtin_fmaxf(b, -448.f), 448.f);
;     c = __builtin_fminf(__builtin_fmaxf(c, -448.f), 448.f); d = __builtin_fminf(__builtin_fmaxf(d, -448.f), 448.f);
;     int w = 0; w = __builtin_amdgcn_cvt_pk_fp8_f32(a, b, w, false); w = __builtin_amdgcn_cvt_pk_fp8_f32(c, d, w, true); return (unsigned)w; }
;     __device__ __forceinline__ void operator()(const f32x4 (&acc)[2][2][4][2], const Unit& u, int wr, int wc, int fr, int fq) const {
;         const int row0 = u.pm * BM + wr * 64 + fr, col0 = u.pn * HALF + wc * 32 + 8 * fq;
;         const float ib = inv * st;
; #pragma unroll
;         for (int ai = 0; ai < 2; ++ai)
; #pragma unroll
;             for (int m = 0; m < 4; ++m) { unsigned char* rowp = O + (size_t)(row0 + ai * HALF + m * 16) * ldc + col0;
;                 const f32x4 a0 = acc[ai][0][m][0] * inv, a1 = acc[ai][0][m][1] * inv, b0 = acc[ai][1][m][0] * ib, b1 = acc[ai][1][m][1] * ib;
;                 u32x2 w;
;                 w.x = cvt4_fp8(silu_mul(a0[0], b0[0]), silu_mul(a0[1], b0[1]), silu_mul(a0[2], b0[2]), silu_mul(a0[3], b0[3]));
;                 w.y = cvt4_fp8(silu_mul(a1[0], b1[0]), silu_mul(a1[1], b1[1]), silu_mul(a1[2], b1[2]), silu_mul(a1[3], b1[3]));
;                 *(u32x2*)rowp = w; }
.LBB0_933:
	v_mov_b32_e32 v20, s44
	v_mov_b32_e32 v24, s46
	v_mul_f32_e32 v24, s44, v24
	v_mul_f32_e32 v20, 0xbfb8aa3b, v20
	v_rcp_f32_e32 v24, v24
	s_nop 1
	v_lshl_add_u32 v6, s14, 8, v183
	v_lshl_or_b32 v2, s10, 7, v215
	v_mov_b64_e32 v[4:5], s[58:59]
	v_ashrrev_i32_e32 v3, 31, v2
	v_mad_i64_i32 v[10:11], s[4:5], v6, s84, v[4:5]
	v_lshl_add_u64 v[10:11], v[10:11], 0, v[2:3]
	v_pk_mul_f32 v[12:13], v[158:159], v[20:21] op_sel_hi:[1,0]
	v_pk_mul_f32 v[14:15], v[160:161], v[20:21] op_sel_hi:[1,0]
	v_pk_mul_f32 v[16:17], v[154:155], v[20:21] op_sel_hi:[1,0]
	v_pk_mul_f32 v[18:19], v[156:157], v[20:21] op_sel_hi:[1,0]
	v_exp_f32_e32 v12, v12
	v_exp_f32_e32 v13, v13
	v_exp_f32_e32 v14, v14
	v_exp_f32_e32 v15, v15
	v_exp_f32_e32 v16, v16
	v_exp_f32_e32 v17, v17
	v_exp_f32_e32 v18, v18
	v_exp_f32_e32 v19, v19
	v_pk_mul_f32 v[158:159], v[158:159], v[126:127]
	v_pk_mul_f32 v[160:161], v[160:161], v[128:129]
	v_pk_mul_f32 v[154:155], v[154:155], v[122:123]
	v_pk_mul_f32 v[156:157], v[156:157], v[124:125]
	v_pk_fma_f32 v[12:13], v[12:13], v[24:25], v[24:25] op_sel_hi:[1,0,0]
	v_pk_fma_f32 v[14:15], v[14:15], v[24:25], v[24:25] op_sel_hi:[1,0,0]
	v_pk_fma_f32 v[16:17], v[16:17], v[24:25], v[24:25] op_sel_hi:[1,0,0]
	v_pk_fma_f32 v[18:19], v[18:19], v[24:25], v[24:25] op_sel_hi:[1,0,0]
	v_rcp_f32_e32 v12, v12
	v_rcp_f32_e32 v13, v13
	v_rcp_f32_e32 v14, v14
	v_rcp_f32_e32 v15, v15
	v_rcp_f32_e32 v16, v16
	v_rcp_f32_e32 v17, v17
	v_rcp_f32_e32 v18, v18
	v_rcp_f32_e32 v19, v19
	v_pk_mul_f32 v[158:159], v[158:159], v[12:13]
	v_pk_mul_f32 v[160:161], v[160:161], v[14:15]
	v_pk_mul_f32 v[154:155], v[154:155], v[16:17]
	v_pk_mul_f32 v[156:157], v[156:157], v[18:19]
	v_med3_f32 v158, v158, s85, v217
	v_med3_f32 v159, v159, s85, v217
	v_med3_f32 v160, v160, s85, v217
	v_med3_f32 v161, v161, s85, v217
	v_med3_f32 v154, v154, s85, v217
	v_med3_f32 v155, v155, s85, v217
	v_med3_f32 v156, v156, s85, v217
	v_med3_f32 v157, v157, s85, v217
	v_cvt_pk_fp8_f32 v8, v158, v159
	v_cvt_pk_fp8_f32 v9, v154, v155
	v_cvt_pk_fp8_f32 v8, v160, v161 op_sel:[0,0,1]
	v_cvt_pk_fp8_f32 v9, v156, v157 op_sel:[0,0,1]
	s_nop 1
	global_store_dwordx2 v[10:11], v[8:9], off
	v_or_b32_e32 v7, 16, v6
	v_mad_i64_i32 v[10:11], s[4:5], v7, s84, v[4:5]
	v_lshl_add_u64 v[10:11], v[10:11], 0, v[2:3]
	v_pk_mul_f32 v[12:13], v[150:151], v[20:21] op_sel_hi:[1,0]
	v_pk_mul_f32 v[14:15], v[152:153], v[20:21] op_sel_hi:[1,0]
	v_pk_mul_f32 v[16:17], v[146:147], v[20:21] op_sel_hi:[1,0]
	v_pk_mul_f32 v[18:19], v[148:149], v[20:21] op_sel_hi:[1,0]
	v_exp_f32_e32 v12, v12
	v_exp_f32_e32 v13, v13
	v_exp_f32_e32 v14, v14
	v_exp_f32_e32 v15, v15
	v_exp_f32_e32 v16, v16
	v_exp_f32_e32 v17, v17
	v_exp_f32_e32 v18, v18
	v_exp_f32_e32 v19, v19
	v_pk_mul_f32 v[150:151], v[150:151], v[118:119]
	v_pk_mul_f32 v[152:153], v[152:153], v[120:121]
	v_pk_mul_f32 v[146:147], v[146:147], v[114:115]
	v_pk_mul_f32 v[148:149], v[148:149], v[116:117]
	v_pk_fma_f32 v[12:13], v[12:13], v[24:25], v[24:25] op_sel_hi:[1,0,0]
	v_pk_fma_f32 v[14:15], v[14:15], v[24:25], v[24:25] op_sel_hi:[1,0,0]
	v_pk_fma_f32 v[16:17], v[16:17], v[24:25], v[24:25] op_sel_hi:[1,0,0]
	v_pk_fma_f32 v[18:19], v[18:19], v[24:25], v[24:25] op_sel_hi:[1,0,0]
	v_rcp_f32_e32 v12, v12
	v_rcp_f32_e32 v13, v13
	v_rcp_f32_e32 v14, v14
	v_rcp_f32_e32 v15, v15
	v_rcp_f32_e32 v16, v16
	v_rcp_f32_e32 v17, v17
	v_rcp_f32_e32 v18, v18
	v_rcp_f32_e32 v19, v19
	v_pk_mul_f32 v[150:151], v[150:151], v[12:13]
	v_pk_mul_f32 v[152:153], v[152:153], v[14:15]
	v_pk_mul_f32 v[146:147], v[146:147], v[16:17]
	v_pk_mul_f32 v[148:149], v[148:149], v[18:19]
	v_med3_f32 v150, v150, s85, v217
	v_med3_f32 v151, v151, s85, v217
	v_med3_f32 v152, v152, s85, v217
	v_med3_f32 v153, v153, s85, v217
	v_med3_f32 v146, v146, s85, v217
	v_med3_f32 v147, v147, s85, v217
	v_med3_f32 v148, v148, s85, v217
	v_med3_f32 v149, v149, s85, v217
	v_cvt_pk_fp8_f32 v8, v150, v151
	v_cvt_pk_fp8_f32 v9, v146, v147
	v_cvt_pk_fp8_f32 v8, v152, v153 op_sel:[0,0,1]
	v_cvt_pk_fp8_f32 v9, v148, v149 op_sel:[0,0,1]
	s_nop 1
	global_store_dwordx2 v[10:11], v[8:9], off
	v_or_b32_e32 v7, 32, v6
	v_mad_i64_i32 v[10:11], s[4:5], v7, s84, v[4:5]
	v_lshl_add_u64 v[10:11], v[10:11], 0, v[2:3]
	v_pk_mul_f32 v[12:13], v[142:143], v[20:21] op_sel_hi:[1,0]
	v_pk_mul_f32 v[14:15], v[144:145], v[20:21] op_sel_hi:[1,0]
	v_pk_mul_f32 v[16:17], v[138:139], v[20:21] op_sel_hi:[1,0]
	v_pk_mul_f32 v[18:19], v[140:141], v[20:21] op_sel_hi:[1,0]
	v_exp_f32_e32 v12, v12
	v_exp_f32_e32 v13, v13
	v_exp_f32_e32 v14, v14
	v_exp_f32_e32 v15, v15
	v_exp_f32_e32 v16, v16
	v_exp_f32_e32 v17, v17
	v_exp_f32_e32 v18, v18
	v_exp_f32_e32 v19, v19
	v_pk_mul_f32 v[142:143], v[142:143], v[110:111]
	v_pk_mul_f32 v[144:145], v[144:145], v[112:113]
	v_pk_mul_f32 v[138:139], v[138:139], v[106:107]
	v_pk_mul_f32 v[140:141], v[140:141], v[108:109]
	v_pk_fma_f32 v[12:13], v[12:13], v[24:25], v[24:25] op_sel_hi:[1,0,0]
	v_pk_fma_f32 v[14:15], v[14:15], v[24:25], v[24:25] op_sel_hi:[1,0,0]
	v_pk_fma_f32 v[16:17], v[16:17], v[24:25], v[24:25] op_sel_hi:[1,0,0]
	v_pk_fma_f32 v[18:19], v[18:19], v[24:25], v[24:25] op_sel_hi:[1,0,0]
	v_rcp_f32_e32 v12, v12
	v_rcp_f32_e32 v13, v13
	v_rcp_f32_e32 v14, v14
	v_rcp_f32_e32 v15, v15
	v_rcp_f32_e32 v16, v16
	v_rcp_f32_e32 v17, v17
	v_rcp_f32_e32 v18, v18
	v_rcp_f32_e32 v19, v19
	v_pk_mul_f32 v[142:143], v[142:143], v[12:13]
	v_pk_mul_f32 v[144:145], v[144:145], v[14:15]
	v_pk_mul_f32 v[138:139], v[138:139], v[16:17]
	v_pk_mul_f32 v[140:141], v[140:141], v[18:19]
	v_med3_f32 v142, v142, s85, v217
	v_med3_f32 v143, v143, s85, v217
	v_med3_f32 v144, v144, s85, v217
	v_med3_f32 v145, v145, s85, v217
	v_med3_f32 v138, v138, s85, v217
; __device__ __forceinline__ float silu_mul(float a, float b) { return a * b * __builtin_amdgcn_rcpf(1.0f + __expf(-a)); }
;     __device__ __forceinline__ void operator()(const f32x4 (&acc)[2][2][4][2], const Unit& u, int wr, int wc, int fr, int fq) const {
;     ...
;         for (int ai = 0; ai < 2; ++ai)
; #pragma unroll
;             for (int m = 0; m < 4; ++m) { unsigned char* rowp = O + (size_t)(row0 + ai * HALF + m * 16) * ldc + col0;
;                 const f32x4 a0 = acc[ai][0][m][0] * inv, a1 = acc[ai][0][m][1] * inv, b0 = acc[ai][1][m][0] * ib, b1 = acc[ai][1][m][1] * ib;
;                 u32x2 w;
;                 w.x = cvt4_fp8(silu_mul(a0[0], b0[0]), silu_mul(a0[1], b0[1]), silu_mul(a0[2], b0[2]), silu_mul(a0[3], b0[3]));
;                 w.y = cvt4_fp8(silu_mul(a1[0], b1[0]), silu_mul(a1[1], b1[1]), silu_mul(a1[2], b1[2]), silu_mul(a1[3], b1[3]));
;                 *(u32x2*)rowp = w; }
	v_med3_f32 v139, v139, s85, v217
	v_med3_f32 v140, v140, s85, v217
	v_med3_f32 v141, v141, s85, v217
	v_cvt_pk_fp8_f32 v8, v142, v143
	v_cvt_pk_fp8_f32 v9, v138, v139
	v_cvt_pk_fp8_f32 v8, v144, v145 op_sel:[0,0,1]
	v_cvt_pk_fp8_f32 v9, v140, v141 op_sel:[0,0,1]
	s_nop 1
	global_store_dwordx2 v[10:11], v[8:9], off
	v_or_b32_e32 v7, 48, v6
	v_mad_i64_i32 v[10:11], s[4:5], v7, s84, v[4:5]
	v_lshl_add_u64 v[10:11], v[10:11], 0, v[2:3]
	v_pk_mul_f32 v[12:13], v[134:135], v[20:21] op_sel_hi:[1,0]
	v_pk_mul_f32 v[14:15], v[136:137], v[20:21] op_sel_hi:[1,0]
	v_pk_mul_f32 v[16:17], v[130:131], v[20:21] op_sel_hi:[1,0]
	v_pk_mul_f32 v[18:19], v[132:133], v[20:21] op_sel_hi:[1,0]
	v_exp_f32_e32 v12, v12
	v_exp_f32_e32 v13, v13
	v_exp_f32_e32 v14, v14
	v_exp_f32_e32 v15, v15
	v_exp_f32_e32 v16, v16
	v_exp_f32_e32 v17, v17
	v_exp_f32_e32 v18, v18
	v_exp_f32_e32 v19, v19
	v_pk_mul_f32 v[134:135], v[134:135], v[102:103]
	v_pk_mul_f32 v[136:137], v[136:137], v[104:105]
	v_pk_mul_f32 v[130:131], v[130:131], v[98:99]
	v_pk_mul_f32 v[132:133], v[132:133], v[100:101]
	v_pk_fma_f32 v[12:13], v[12:13], v[24:25], v[24:25] op_sel_hi:[1,0,0]
	v_pk_fma_f32 v[14:15], v[14:15], v[24:25], v[24:25] op_sel_hi:[1,0,0]
	v_pk_fma_f32 v[16:17], v[16:17], v[24:25], v[24:25] op_sel_hi:[1,0,0]
	v_pk_fma_f32 v[18:19], v[18:19], v[24:25], v[24:25] op_sel_hi:[1,0,0]
	v_rcp_f32_e32 v12, v12
	v_rcp_f32_e32 v13, v13
	v_rcp_f32_e32 v14, v14
	v_rcp_f32_e32 v15, v15
	v_rcp_f32_e32 v16, v16
	v_rcp_f32_e32 v17, v17
	v_rcp_f32_e32 v18, v18
	v_rcp_f32_e32 v19, v19
	v_pk_mul_f32 v[134:135], v[134:135], v[12:13]
	v_pk_mul_f32 v[136:137], v[136:137], v[14:15]
	v_pk_mul_f32 v[130:131], v[130:131], v[16:17]
	v_pk_mul_f32 v[132:133], v[132:133], v[18:19]
	v_med3_f32 v134, v134, s85, v217
	v_med3_f32 v135, v135, s85, v217
	v_med3_f32 v136, v136, s85, v217
	v_med3_f32 v137, v137, s85, v217
	v_med3_f32 v130, v130, s85, v217
	v_med3_f32 v131, v131, s85, v217
	v_med3_f32 v132, v132, s85, v217
	v_med3_f32 v133, v133, s85, v217
	v_cvt_pk_fp8_f32 v8, v134, v135
	v_cvt_pk_fp8_f32 v9, v130, v131
	v_cvt_pk_fp8_f32 v8, v136, v137 op_sel:[0,0,1]
	v_cvt_pk_fp8_f32 v9, v132, v133 op_sel:[0,0,1]
	s_nop 1
	global_store_dwordx2 v[10:11], v[8:9], off
	v_add_u32_e32 v7, 0x80, v6
	v_mad_i64_i32 v[10:11], s[4:5], v7, s84, v[4:5]
	v_lshl_add_u64 v[10:11], v[10:11], 0, v[2:3]
	v_pk_mul_f32 v[12:13], v[94:95], v[20:21] op_sel_hi:[1,0]
	v_pk_mul_f32 v[14:15], v[96:97], v[20:21] op_sel_hi:[1,0]
	v_pk_mul_f32 v[16:17], v[90:91], v[20:21] op_sel_hi:[1,0]
	v_pk_mul_f32 v[18:19], v[92:93], v[20:21] op_sel_hi:[1,0]
	v_exp_f32_e32 v12, v12
	v_exp_f32_e32 v13, v13
	v_exp_f32_e32 v14, v14
	v_exp_f32_e32 v15, v15
	v_exp_f32_e32 v16, v16
	v_exp_f32_e32 v17, v17
	v_exp_f32_e32 v18, v18
	v_exp_f32_e32 v19, v19
	v_pk_mul_f32 v[94:95], v[94:95], v[62:63]
	v_pk_mul_f32 v[96:97], v[96:97], v[64:65]
	v_pk_mul_f32 v[90:91], v[90:91], v[58:59]
	v_pk_mul_f32 v[92:93], v[92:93], v[60:61]
	v_pk_fma_f32 v[12:13], v[12:13], v[24:25], v[24:25] op_sel_hi:[1,0,0]
	v_pk_fma_f32 v[14:15], v[14:15], v[24:25], v[24:25] op_sel_hi:[1,0,0]
	v_pk_fma_f32 v[16:17], v[16:17], v[24:25], v[24:25] op_sel_hi:[1,0,0]
	v_pk_fma_f32 v[18:19], v[18:19], v[24:25], v[24:25] op_sel_hi:[1,0,0]
	v_rcp_f32_e32 v12, v12
	v_rcp_f32_e32 v13, v13
	v_rcp_f32_e32 v14, v14
	v_rcp_f32_e32 v15, v15
	v_rcp_f32_e32 v16, v16
	v_rcp_f32_e32 v17, v17
	v_rcp_f32_e32 v18, v18
	v_rcp_f32_e32 v19, v19
	v_pk_mul_f32 v[94:95], v[94:95], v[12:13]
	v_pk_mul_f32 v[96:97], v[96:97], v[14:15]
	v_pk_mul_f32 v[90:91], v[90:91], v[16:17]
	v_pk_mul_f32 v[92:93], v[92:93], v[18:19]
	v_med3_f32 v94, v94, s85, v217
	v_med3_f32 v95, v95, s85, v217
	v_med3_f32 v96, v96, s85, v217
	v_med3_f32 v97, v97, s85, v217
	v_med3_f32 v90, v90, s85, v217
	v_med3_f32 v91, v91, s85, v217
	v_med3_f32 v92, v92, s85, v217
	v_med3_f32 v93, v93, s85, v217
	v_cvt_pk_fp8_f32 v8, v94, v95
	v_cvt_pk_fp8_f32 v9, v90, v91
	v_cvt_pk_fp8_f32 v8, v96, v97 op_sel:[0,0,1]
	v_cvt_pk_fp8_f32 v9, v92, v93 op_sel:[0,0,1]
	s_nop 1
	global_store_dwordx2 v[10:11], v[8:9], off
	v_add_u32_e32 v7, 0x90, v6
	v_mad_i64_i32 v[10:11], s[4:5], v7, s84, v[4:5]
	v_lshl_add_u64 v[10:11], v[10:11], 0, v[2:3]
	v_pk_mul_f32 v[12:13], v[86:87], v[20:21] op_sel_hi:[1,0]
	v_pk_mul_f32 v[14:15], v[88:89], v[20:21] op_sel_hi:[1,0]
	v_pk_mul_f32 v[16:17], v[82:83], v[20:21] op_sel_hi:[1,0]
	v_pk_mul_f32 v[18:19], v[84:85], v[20:21] op_sel_hi:[1,0]
	v_exp_f32_e32 v12, v12
	v_exp_f32_e32 v13, v13
	v_exp_f32_e32 v14, v14
	v_exp_f32_e32 v15, v15
	v_exp_f32_e32 v16, v16
	v_exp_f32_e32 v17, v17
	v_exp_f32_e32 v18, v18
	v_exp_f32_e32 v19, v19
	v_pk_mul_f32 v[86:87], v[86:87], v[54:55]
	v_pk_mul_f32 v[88:89], v[88:89], v[56:57]
	v_pk_mul_f32 v[82:83], v[82:83], v[50:51]
	v_pk_mul_f32 v[84:85], v[84:85], v[52:53]
	v_pk_fma_f32 v[12:13], v[12:13], v[24:25], v[24:25] op_sel_hi:[1,0,0]
; __device__ __forceinline__ float silu_mul(float a, float b) { return a * b * __builtin_amdgcn_rcpf(1.0f + __expf(-a)); }
;     __device__ __forceinline__ void operator()(const f32x4 (&acc)[2][2][4][2], const Unit& u, int wr, int wc, int fr, int fq) const {
;     ...
;         for (int ai = 0; ai < 2; ++ai)
; #pragma unroll
;             for (int m = 0; m < 4; ++m) { unsigned char* rowp = O + (size_t)(row0 + ai * HALF + m * 16) * ldc + col0;
;                 const f32x4 a0 = acc[ai][0][m][0] * inv, a1 = acc[ai][0][m][1] * inv, b0 = acc[ai][1][m][0] * ib, b1 = acc[ai][1][m][1] * ib;
;                 u32x2 w;
;                 w.x = cvt4_fp8(silu_mul(a0[0], b0[0]), silu_mul(a0[1], b0[1]), silu_mul(a0[2], b0[2]), silu_mul(a0[3], b0[3]));
;                 w.y = cvt4_fp8(silu_mul(a1[0], b1[0]), silu_mul(a1[1], b1[1]), silu_mul(a1[2], b1[2]), silu_mul(a1[3], b1[3]));
;                 *(u32x2*)rowp = w; }
	v_pk_fma_f32 v[14:15], v[14:15], v[24:25], v[24:25] op_sel_hi:[1,0,0]
	v_pk_fma_f32 v[16:17], v[16:17], v[24:25], v[24:25] op_sel_hi:[1,0,0]
	v_pk_fma_f32 v[18:19], v[18:19], v[24:25], v[24:25] op_sel_hi:[1,0,0]
	v_rcp_f32_e32 v12, v12
	v_rcp_f32_e32 v13, v13
	v_rcp_f32_e32 v14, v14
	v_rcp_f32_e32 v15, v15
	v_rcp_f32_e32 v16, v16
	v_rcp_f32_e32 v17, v17
	v_rcp_f32_e32 v18, v18
	v_rcp_f32_e32 v19, v19
	v_pk_mul_f32 v[86:87], v[86:87], v[12:13]
	v_pk_mul_f32 v[88:89], v[88:89], v[14:15]
	v_pk_mul_f32 v[82:83], v[82:83], v[16:17]
	v_pk_mul_f32 v[84:85], v[84:85], v[18:19]
	v_med3_f32 v86, v86, s85, v217
	v_med3_f32 v87, v87, s85, v217
	v_med3_f32 v88, v88, s85, v217
	v_med3_f32 v89, v89, s85, v217
	v_med3_f32 v82, v82, s85, v217
	v_med3_f32 v83, v83, s85, v217
	v_med3_f32 v84, v84, s85, v217
	v_med3_f32 v85, v85, s85, v217
	v_cvt_pk_fp8_f32 v8, v86, v87
	v_cvt_pk_fp8_f32 v9, v82, v83
	v_cvt_pk_fp8_f32 v8, v88, v89 op_sel:[0,0,1]
	v_cvt_pk_fp8_f32 v9, v84, v85 op_sel:[0,0,1]
	s_nop 1
	global_store_dwordx2 v[10:11], v[8:9], off
	v_add_u32_e32 v7, 0xa0, v6
	v_mad_i64_i32 v[10:11], s[4:5], v7, s84, v[4:5]
	v_lshl_add_u64 v[10:11], v[10:11], 0, v[2:3]
	v_pk_mul_f32 v[12:13], v[78:79], v[20:21] op_sel_hi:[1,0]
	v_pk_mul_f32 v[14:15], v[80:81], v[20:21] op_sel_hi:[1,0]
	v_pk_mul_f32 v[16:17], v[74:75], v[20:21] op_sel_hi:[1,0]
	v_pk_mul_f32 v[18:19], v[76:77], v[20:21] op_sel_hi:[1,0]
	v_exp_f32_e32 v12, v12
	v_exp_f32_e32 v13, v13
	v_exp_f32_e32 v14, v14
	v_exp_f32_e32 v15, v15
	v_exp_f32_e32 v16, v16
	v_exp_f32_e32 v17, v17
	v_exp_f32_e32 v18, v18
	v_exp_f32_e32 v19, v19
	v_pk_mul_f32 v[78:79], v[78:79], v[46:47]
	v_pk_mul_f32 v[80:81], v[80:81], v[48:49]
	v_pk_mul_f32 v[74:75], v[74:75], v[42:43]
	v_pk_mul_f32 v[76:77], v[76:77], v[44:45]
	v_pk_fma_f32 v[12:13], v[12:13], v[24:25], v[24:25] op_sel_hi:[1,0,0]
	v_pk_fma_f32 v[14:15], v[14:15], v[24:25], v[24:25] op_sel_hi:[1,0,0]
	v_pk_fma_f32 v[16:17], v[16:17], v[24:25], v[24:25] op_sel_hi:[1,0,0]
	v_pk_fma_f32 v[18:19], v[18:19], v[24:25], v[24:25] op_sel_hi:[1,0,0]
	v_rcp_f32_e32 v12, v12
	v_rcp_f32_e32 v13, v13
	v_rcp_f32_e32 v14, v14
	v_rcp_f32_e32 v15, v15
	v_rcp_f32_e32 v16, v16
	v_rcp_f32_e32 v17, v17
	v_rcp_f32_e32 v18, v18
	v_rcp_f32_e32 v19, v19
	v_pk_mul_f32 v[78:79], v[78:79], v[12:13]
	v_pk_mul_f32 v[80:81], v[80:81], v[14:15]
	v_pk_mul_f32 v[74:75], v[74:75], v[16:17]
	v_pk_mul_f32 v[76:77], v[76:77], v[18:19]
	v_med3_f32 v78, v78, s85, v217
	v_med3_f32 v79, v79, s85, v217
	v_med3_f32 v80, v80, s85, v217
	v_med3_f32 v81, v81, s85, v217
	v_med3_f32 v74, v74, s85, v217
	v_med3_f32 v75, v75, s85, v217
	v_med3_f32 v76, v76, s85, v217
	v_med3_f32 v77, v77, s85, v217
	v_cvt_pk_fp8_f32 v8, v78, v79
	v_cvt_pk_fp8_f32 v9, v74, v75
	v_cvt_pk_fp8_f32 v8, v80, v81 op_sel:[0,0,1]
	v_cvt_pk_fp8_f32 v9, v76, v77 op_sel:[0,0,1]
	s_nop 1
	global_store_dwordx2 v[10:11], v[8:9], off
	v_add_u32_e32 v22, 0xb0, v6
	v_mad_i64_i32 v[4:5], s[4:5], v22, s84, v[4:5]
	v_lshl_add_u64 v[2:3], v[4:5], 0, v[2:3]
	v_pk_mul_f32 v[12:13], v[70:71], v[20:21] op_sel_hi:[1,0]
	v_pk_mul_f32 v[14:15], v[72:73], v[20:21] op_sel_hi:[1,0]
	v_pk_mul_f32 v[16:17], v[66:67], v[20:21] op_sel_hi:[1,0]
	v_pk_mul_f32 v[18:19], v[68:69], v[20:21] op_sel_hi:[1,0]
	v_exp_f32_e32 v12, v12
	v_exp_f32_e32 v13, v13
	v_exp_f32_e32 v14, v14
	v_exp_f32_e32 v15, v15
	v_exp_f32_e32 v16, v16
	v_exp_f32_e32 v17, v17
	v_exp_f32_e32 v18, v18
	v_exp_f32_e32 v19, v19
	v_pk_mul_f32 v[70:71], v[70:71], v[38:39]
	v_pk_mul_f32 v[72:73], v[72:73], v[40:41]
	v_pk_mul_f32 v[66:67], v[66:67], v[34:35]
	v_pk_mul_f32 v[68:69], v[68:69], v[36:37]
	v_pk_fma_f32 v[12:13], v[12:13], v[24:25], v[24:25] op_sel_hi:[1,0,0]
	v_pk_fma_f32 v[14:15], v[14:15], v[24:25], v[24:25] op_sel_hi:[1,0,0]
	v_pk_fma_f32 v[16:17], v[16:17], v[24:25], v[24:25] op_sel_hi:[1,0,0]
	v_pk_fma_f32 v[18:19], v[18:19], v[24:25], v[24:25] op_sel_hi:[1,0,0]
	v_rcp_f32_e32 v12, v12
	v_rcp_f32_e32 v13, v13
	v_rcp_f32_e32 v14, v14
	v_rcp_f32_e32 v15, v15
	v_rcp_f32_e32 v16, v16
	v_rcp_f32_e32 v17, v17
	v_rcp_f32_e32 v18, v18
	v_rcp_f32_e32 v19, v19
	v_pk_mul_f32 v[70:71], v[70:71], v[12:13]
	v_pk_mul_f32 v[72:73], v[72:73], v[14:15]
	v_pk_mul_f32 v[66:67], v[66:67], v[16:17]
	v_pk_mul_f32 v[68:69], v[68:69], v[18:19]
	v_med3_f32 v70, v70, s85, v217
	v_med3_f32 v71, v71, s85, v217
	v_med3_f32 v72, v72, s85, v217
	v_med3_f32 v73, v73, s85, v217
	v_med3_f32 v66, v66, s85, v217
	v_med3_f32 v67, v67, s85, v217
	v_med3_f32 v68, v68, s85, v217
	v_med3_f32 v69, v69, s85, v217
	v_cvt_pk_fp8_f32 v6, v70, v71
	v_cvt_pk_fp8_f32 v7, v66, v67
	v_cvt_pk_fp8_f32 v6, v72, v73 op_sel:[0,0,1]
	v_cvt_pk_fp8_f32 v7, v68, v69 op_sel:[0,0,1]
	s_nop 1
	global_store_dwordx2 v[2:3], v[6:7], off
	s_andn2_b64 vcc, exec, s[62:63]
	s_cbranch_vccnz .LBB0_913
	s_branch .LBB0_931
